# grid barrier: non-leader workgroups wait on the top-level generation word directly (one relay hop less)
# baseline (speedup 1.0000x reference)
.LBB0_1292:
	s_or_b64 exec, exec, s[10:11]
	v_cvt_f32_u32_e32 v5, v3
	s_waitcnt vmcnt(0)
	v_readfirstlane_b32 s0, v4
	v_sub_u32_e32 v4, 0, v3
	v_rcp_iflag_f32_e32 v5, v5
	v_add_u32_e32 v6, s0, v0
	v_mul_f32_e32 v5, 0x4f7ffffe, v5
	v_cvt_u32_f32_e32 v5, v5
	v_mul_lo_u32 v0, v4, v5
	v_mul_hi_u32 v0, v5, v0
	v_add_u32_e32 v0, v5, v0
	v_mul_hi_u32 v0, v6, v0
	v_mul_lo_u32 v4, v0, v3
	v_sub_u32_e32 v4, v6, v4
	v_add_u32_e32 v5, 1, v0
	v_cmp_ge_u32_e32 vcc, v4, v3
	s_nop 1
	v_cndmask_b32_e32 v0, v0, v5, vcc
	v_sub_u32_e32 v5, v4, v3
	v_cndmask_b32_e32 v4, v4, v5, vcc
	v_add_u32_e32 v5, 1, v0
	v_cmp_ge_u32_e32 vcc, v4, v3
	v_add_u32_e32 v4, 1, v6
	s_nop 0
	v_cndmask_b32_e32 v0, v0, v5, vcc
	v_mul_lo_u32 v5, v3, v0
	v_add_u32_e32 v3, v5, v3
	v_cmp_ne_u32_e32 vcc, v4, v3
	s_and_saveexec_b64 s[8:9], vcc
	s_xor_b64 s[8:9], exec, s[8:9]
	s_cbranch_execz .LBB0_1306
	s_waitcnt lgkmcnt(0)
	v_readlane_b32 s14, v254, 9
	v_readlane_b32 s15, v254, 10
	s_add_u32 s14, s14, 0x4500
	s_addc_u32 s15, s15, 0
	global_load_dword v2, v1, s[14:15] sc1
	s_waitcnt vmcnt(0)
	v_cmp_eq_u32_e32 vcc, v2, v0
	s_and_saveexec_b64 s[10:11], vcc
	s_cbranch_execz .LBB0_1305
	v_readlane_b32 s12, v254, 9
	v_readlane_b32 s13, v254, 10
	s_add_u32 s12, s12, 0x1200
	s_addc_u32 s13, s13, 0
	s_mov_b32 s0, 1
	s_mov_b64 s[16:17], 0
	s_branch .LBB0_1296
